# grid barrier one hop shorter: XCD-last adds its block count to one cross-XCD word without return, all blocks poll that word (no top returning atomic, no generation bumps)
# speedup vs baseline: 1.0035x; 1.0015x over previous
; #define LAS __attribute__((address_space(3)))
; __device__ __forceinline__ unsigned xb_add(unsigned* p, unsigned v) { return __hip_atomic_fetch_add(p, v, __ATOMIC_RELAXED, __HIP_MEMORY_SCOPE_AGENT); }
; __device__ __forceinline__ unsigned xb_xcc_id() { return (unsigned)__builtin_amdgcn_s_getreg((3 << 11) | 20) & 0xFu; }
; __device__ __forceinline__ XcdBarrier xcd_barrier_post(unsigned* bar, volatile LAS unsigned* st) {
;     XcdBarrier b; b.bar = bar; b.x = xb_xcc_id(); b.st = st;
;     if (threadIdx.x == 0) (void)xb_add(&bar[XB_XCNT(b.x)], 1u);
;     return b;
; }
; __global__ void __launch_bounds__(NTHREADS, 2) mega(Params P, int ph_lo, int ph_hi) {
;     extern __shared__ __attribute__((aligned(16))) unsigned char lds_raw[];
;     LAS unsigned char* lds = (LAS unsigned char*)lds_raw;
;     cg::grid_group grid = cg::this_grid();
;     const int tid = threadIdx.x, lane = tid & 63, wid = __builtin_amdgcn_readfirstlane(tid >> 6);
;     const int G = gridDim.x, gw = blockIdx.x * NWAVES + wid, NGW = G * NWAVES;
;     unsigned char* ws = P.ws;
;     volatile LAS unsigned* MISC = (volatile LAS unsigned*)(lds + 131072);
;     if (tid < 4) MISC[tid] = 0u;
;     __syncthreads();
;     const XcdBarrier xbar = xcd_barrier_post((unsigned*)(ws + OFF_BAR), MISC);
_Z4mega6Paramsii:
	s_load_dwordx8 s[4:11], s[0:1], 0xc0
	s_load_dword s90, s[0:1], 0x100
	s_load_dwordx4 s[84:87], s[0:1], 0xe0
	s_load_dwordx2 s[96:97], s[0:1], 0xf8
	s_add_u32 s20, s0, 0xf8
	v_and_b32_e32 v209, 0x3ff, v0
	s_mov_b32 s33, s2
	s_waitcnt lgkmcnt(0)
	v_writelane_b32 v254, s4, 0
	s_addc_u32 s21, s1, 0
	v_readfirstlane_b32 s92, v209
	v_writelane_b32 v254, s5, 1
	v_writelane_b32 v254, s6, 2
	v_writelane_b32 v254, s7, 3
	v_writelane_b32 v254, s8, 4
	v_writelane_b32 v254, s9, 5
	v_writelane_b32 v254, s10, 6
	v_cmp_gt_u32_e32 vcc, 4, v209
	v_writelane_b32 v254, s11, 7
	s_and_saveexec_b64 s[2:3], vcc
	v_lshl_add_u32 v1, v209, 2, 0
	v_add_u32_e32 v1, 0x20000, v1
	v_mov_b32_e32 v2, 0
	ds_write_b32 v1, v2
	s_or_b64 exec, exec, s[2:3]
	s_waitcnt lgkmcnt(0)
	s_barrier
	s_mov_b32 s100, 0
	s_nop 3
	v_writelane_b32 v254, s100, 48
	s_add_u32 s66, s86, 0x2b62800
	s_getreg_b32 s2, hwreg(HW_REG_XCC_ID, 0, 4)
	s_addc_u32 s67, s87, 0
	s_and_b32 s65, s2, 15
	v_cmp_eq_u32_e64 s[4:5], 0, v209
	s_mov_b64 s[2:3], exec
	s_nop 0
	v_writelane_b32 v254, s4, 8
	s_nop 1
	v_writelane_b32 v254, s5, 9
	s_and_b64 s[4:5], s[2:3], s[4:5]
	s_mov_b64 exec, s[4:5]
	s_cbranch_execz .LBB0_5
	s_mov_b64 s[4:5], exec
	v_mbcnt_lo_u32_b32 v1, s4, 0
	v_mbcnt_hi_u32_b32 v1, s5, v1
	v_cmp_eq_u32_e32 vcc, 0, v1
	s_and_b64 s[6:7], exec, vcc
	s_mov_b64 exec, s[6:7]
	s_cbranch_execz .LBB0_5
	s_lshl_b32 s6, s65, 8
	s_bcnt1_i32_b64 s4, s[4:5]
	v_mov_b32_e32 v1, s6
	v_mov_b32_e32 v2, s4
	global_atomic_add v1, v2, s[66:67] offset:1024

; __device__ __forceinline__ unsigned xb_ld(unsigned* p)              { return __hip_atomic_load(p, __ATOMIC_RELAXED, __HIP_MEMORY_SCOPE_AGENT); }
; __device__ __forceinline__ unsigned xb_add(unsigned* p, unsigned v) { return __hip_atomic_fetch_add(p, v, __ATOMIC_RELAXED, __HIP_MEMORY_SCOPE_AGENT); }
; __device__ __forceinline__ void xcd_barrier_complete(unsigned* bar, unsigned x, unsigned& nloc, unsigned& nx) {
;     const unsigned G = gridDim.x * gridDim.y * gridDim.z;
;     unsigned sum, cnt, mine, sp = 0u;
;     for (;;) {
;         sum = 0u; cnt = 0u; mine = 0u;
; #pragma unroll
;         for (unsigned j = 0; j < 16; ++j) { const unsigned c = xb_ld(&bar[XB_XCNT(j)]); sum += c; cnt += (c > 0u) ? 1u : 0u; mine = (j == x) ? c : mine; }
;         if (sum == G) break;
;         __builtin_amdgcn_s_sleep(1);
;         if ((++sp & 255u) == 0u) { if (xb_ld(&bar[XB_TMO])) break; if (sp > XB_SPIN_CAP) { atomicAdd(&bar[XB_TMO], 1u); break; } }
;     }
;     nloc = mine > 0u ? mine : 1u; nx = cnt > 0u ? cnt : 1u;
; }
; __device__ __forceinline__ void xcd_barrier(const XcdBarrier& b) {
;     asm volatile("s_waitcnt vmcnt(0)" ::: "memory");
;     __syncthreads();
;     if (threadIdx.x == 0) {
;         unsigned* bar = b.bar;
;         __builtin_amdgcn_s_waitcnt(0);
;         unsigned nloc = b.st[0], nx = b.st[1];
;         if (nloc == 0u) { xcd_barrier_complete(bar, b.x, nloc, nx); b.st[0] = nloc; b.st[1] = nx; }
;         const unsigned old = xb_add(&bar[XB_XSUB(b.x)], 1u);
;         const unsigned gen = old / nloc;
;         if (old + 1u == (gen + 1u) * nloc) {
;             __builtin_amdgcn_fence(__ATOMIC_RELEASE, "agent");
;             asm volatile("s_waitcnt vmcnt(0)" ::: "memory");
;             const unsigned og = xb_add(&bar[XB_TOP], 1u);
;             const unsigned tg = og / nx;
;             if (og + 1u == (tg + 1u) * nx) xb_add(&bar[XB_TOPGEN], 1u);
;             else XB_SPIN(xb_ld(&bar[XB_TOPGEN]) == tg, bar);
;             __builtin_amdgcn_fence(__ATOMIC_ACQUIRE, "agent");
;             xb_add(&bar[XB_XGEN(b.x)], 1u);
;             asm volatile("s_waitcnt vmcnt(0)" ::: "memory");
;         } else {
;             XB_SPIN(xb_ld(&bar[XB_XGEN(b.x)]) == gen, bar);
;             __builtin_amdgcn_fence(__ATOMIC_ACQUIRE, "agent");
;             asm volatile("s_waitcnt vmcnt(0)" ::: "memory");
;         }
;     }
;     __syncthreads();
; }
.LBB0_134:
	s_cmp_lt_u32 s89, 2
	s_cbranch_scc1 .LBB0_188
	s_waitcnt vmcnt(0)
	s_barrier
	s_mov_b64 s[0:1], exec
	v_readlane_b32 s2, v254, 8
	v_readlane_b32 s3, v254, 9
	s_and_b64 s[2:3], s[0:1], s[2:3]
	s_mov_b64 exec, s[2:3]
	s_cbranch_execz .LBB0_187
	v_readlane_b32 s8, v254, 48
	s_mul_i32 s9, s97, s96
	s_mul_i32 s9, s9, s90
	s_cmp_lg_u32 s8, 0
	s_cbranch_scc1 .Lmy_sm0_have
	s_mov_b64 exec, 0xffff
	v_lshlrev_b32_e32 v0, 8, v208
	v_add_u32_e32 v0, 0x400, v0
	s_mov_b32 s5, 0
.Lmy_sm0_cen:
	global_load_dword v1, v0, s[66:67] sc1
	s_waitcnt vmcnt(0)
	v_mov_b32_e32 v2, v1
	s_nop 1
	v_add_u32_dpp v2, v1, v2 row_shr:1 row_mask:0xf bank_mask:0xf
	s_nop 1
	v_mov_b32_e32 v3, v2
	s_nop 1
	v_add_u32_dpp v3, v2, v3 row_shr:2 row_mask:0xf bank_mask:0xf
	s_nop 1
	v_mov_b32_e32 v4, v3
	s_nop 1
	v_add_u32_dpp v4, v3, v4 row_shr:4 row_mask:0xf bank_mask:0xf
	s_nop 1
	v_mov_b32_e32 v5, v4
	s_nop 1
	v_add_u32_dpp v5, v4, v5 row_shr:8 row_mask:0xf bank_mask:0xf
	s_nop 1
	v_readlane_b32 s4, v5, 15
	s_cmp_eq_u32 s4, s9
	s_cbranch_scc1 .Lmy_sm0_cend
	s_sleep 1
	s_add_i32 s5, s5, 1
	s_cmp_lt_u32 s5, 0x80000
	s_cbranch_scc1 .Lmy_sm0_cen
.Lmy_sm0_cend:
	v_readlane_b32 s8, v1, s65
	s_max_u32 s8, s8, 1
	s_mov_b64 exec, 1
	s_nop 3
	v_writelane_b32 v254, s8, 48
.Lmy_sm0_have:
	s_add_i32 s100, s100, s9
	s_lshl_b32 s4, s65, 8
	s_addk_i32 s4, 0x1400
	v_mov_b32_e32 v0, s4
	v_mov_b32_e32 v1, 1
	s_waitcnt vmcnt(0) lgkmcnt(0)
	global_atomic_add v1, v0, v1, s[66:67] sc0
	s_waitcnt vmcnt(0)
	buffer_inv sc1
	v_readfirstlane_b32 s4, v1
	s_add_i32 s4, s4, 1
	s_mul_i32 s4, s4, s9
	s_mul_i32 s5, s100, s8
	s_cmp_lg_u32 s4, s5
	s_cbranch_scc1 .Lmy_sm0_wait
	buffer_wbl2 sc1
	v_mov_b32_e32 v0, 0x3400
	v_mov_b32_e32 v1, s8
	s_waitcnt vmcnt(0)
	global_atomic_add v0, v1, s[66:67]
.Lmy_sm0_wait:
	v_mov_b32_e32 v0, 0x3400
	s_mov_b32 s5, 0
.Lmy_sm0_poll:
	global_load_dword v1, v0, s[66:67] sc1
	s_waitcnt vmcnt(0)
	v_readfirstlane_b32 s4, v1
	s_cmp_ge_u32 s4, s100
	s_cbranch_scc1 .Lmy_sm0_done
	s_sleep 1
	s_add_i32 s5, s5, 1
	s_cmp_lt_u32 s5, 0x80000
	s_cbranch_scc1 .Lmy_sm0_poll
.Lmy_sm0_done:
.LBB0_187:
	s_or_b64 exec, exec, s[0:1]
	s_waitcnt lgkmcnt(0)
	s_barrier

; __device__ __forceinline__ void xcd_barrier(const XcdBarrier& b) {
;     asm volatile("s_waitcnt vmcnt(0)" ::: "memory");
;     __syncthreads();
;     if (threadIdx.x == 0) {
;         unsigned* bar = b.bar;
;         __builtin_amdgcn_s_waitcnt(0);
;         unsigned nloc = b.st[0], nx = b.st[1];
;         if (nloc == 0u) { xcd_barrier_complete(bar, b.x, nloc, nx); b.st[0] = nloc; b.st[1] = nx; }
.LBB0_236:
	s_cmp_lt_u32 s89, 3
	s_cbranch_scc1 .LBB0_290
	s_waitcnt vmcnt(0)
	s_waitcnt vmcnt(0)
	s_barrier
	s_mov_b64 s[0:1], exec
	v_readlane_b32 s2, v254, 8
	v_readlane_b32 s3, v254, 9
	s_and_b64 s[2:3], s[0:1], s[2:3]
	s_mov_b64 exec, s[2:3]
	s_cbranch_execz .LBB0_289
	v_readlane_b32 s8, v254, 48
	s_mul_i32 s9, s97, s96
	s_mul_i32 s9, s9, s90
	s_cmp_lg_u32 s8, 0
	s_cbranch_scc1 .Lmy_sm1_have
	s_mov_b64 exec, 0xffff
	v_lshlrev_b32_e32 v0, 8, v208
	v_add_u32_e32 v0, 0x400, v0
	s_mov_b32 s5, 0

; __device__ __forceinline__ void xcd_barrier(const XcdBarrier& b) {
;     asm volatile("s_waitcnt vmcnt(0)" ::: "memory");
;     __syncthreads();
;     if (threadIdx.x == 0) {
;         unsigned* bar = b.bar;
;         __builtin_amdgcn_s_waitcnt(0);
;         unsigned nloc = b.st[0], nx = b.st[1];
;         if (nloc == 0u) { xcd_barrier_complete(bar, b.x, nloc, nx); b.st[0] = nloc; b.st[1] = nx; }
.LBB0_346:
	s_cmp_lt_i32 s89, 4
	s_cbranch_scc1 .LBB0_400
	s_waitcnt vmcnt(0)
	s_waitcnt vmcnt(0) lgkmcnt(0)
	s_barrier
	s_mov_b64 s[0:1], exec
	v_readlane_b32 s2, v254, 8
	v_readlane_b32 s3, v254, 9
	s_and_b64 s[2:3], s[0:1], s[2:3]
	s_mov_b64 exec, s[2:3]
	s_cbranch_execz .LBB0_399
	v_readlane_b32 s8, v254, 48
	s_mul_i32 s9, s97, s96
	s_mul_i32 s9, s9, s90
	s_cmp_lg_u32 s8, 0
	s_cbranch_scc1 .Lmy_sm2_have
	s_mov_b64 exec, 0xffff
	v_lshlrev_b32_e32 v0, 8, v208
	v_add_u32_e32 v0, 0x400, v0
	s_mov_b32 s5, 0

; __device__ __forceinline__ void xcd_barrier(const XcdBarrier& b) {
;     asm volatile("s_waitcnt vmcnt(0)" ::: "memory");
;     __syncthreads();
;     if (threadIdx.x == 0) {
;         unsigned* bar = b.bar;
;         __builtin_amdgcn_s_waitcnt(0);
;         unsigned nloc = b.st[0], nx = b.st[1];
;         if (nloc == 0u) { xcd_barrier_complete(bar, b.x, nloc, nx); b.st[0] = nloc; b.st[1] = nx; }
.LBB0_466:
	s_cmp_lt_u32 s89, 6
	s_cbranch_scc1 .LBB0_520
	s_waitcnt vmcnt(0)
	s_waitcnt vmcnt(0) lgkmcnt(0)
	s_barrier
	s_mov_b64 s[0:1], exec
	v_readlane_b32 s2, v254, 8
	v_readlane_b32 s3, v254, 9
	s_and_b64 s[2:3], s[0:1], s[2:3]
	s_mov_b64 exec, s[2:3]
	s_cbranch_execz .LBB0_519
	v_readlane_b32 s8, v254, 48
	s_mul_i32 s9, s97, s96
	s_mul_i32 s9, s9, s90
	s_cmp_lg_u32 s8, 0
	s_cbranch_scc1 .Lmy_sm3_have
	s_mov_b64 exec, 0xffff
	v_lshlrev_b32_e32 v0, 8, v208
	v_add_u32_e32 v0, 0x400, v0
	s_mov_b32 s5, 0

; __device__ __forceinline__ void xcd_barrier(const XcdBarrier& b) {
;     asm volatile("s_waitcnt vmcnt(0)" ::: "memory");
;     __syncthreads();
;     if (threadIdx.x == 0) {
;         unsigned* bar = b.bar;
;         __builtin_amdgcn_s_waitcnt(0);
;         unsigned nloc = b.st[0], nx = b.st[1];
;         if (nloc == 0u) { xcd_barrier_complete(bar, b.x, nloc, nx); b.st[0] = nloc; b.st[1] = nx; }
.LBB0_559:
	s_cmp_lt_i32 s89, 7
	s_cbranch_scc1 .LBB0_613
	s_waitcnt vmcnt(0)
	s_waitcnt vmcnt(0) lgkmcnt(0)
	s_barrier
	s_mov_b64 s[0:1], exec
	v_readlane_b32 s2, v254, 8
	v_readlane_b32 s3, v254, 9
	s_and_b64 s[2:3], s[0:1], s[2:3]
	s_mov_b64 exec, s[2:3]
	s_cbranch_execz .LBB0_612
	v_readlane_b32 s8, v254, 48
	s_mul_i32 s9, s97, s96
	s_mul_i32 s9, s9, s90
	s_cmp_lg_u32 s8, 0
	s_cbranch_scc1 .Lmy_sm4_have
	s_mov_b64 exec, 0xffff
	v_lshlrev_b32_e32 v0, 8, v208
	v_add_u32_e32 v0, 0x400, v0
	s_mov_b32 s5, 0

; __device__ __forceinline__ void xcd_barrier(const XcdBarrier& b) {
;     asm volatile("s_waitcnt vmcnt(0)" ::: "memory");
;     __syncthreads();
;     if (threadIdx.x == 0) {
;         unsigned* bar = b.bar;
;         __builtin_amdgcn_s_waitcnt(0);
;         unsigned nloc = b.st[0], nx = b.st[1];
;         if (nloc == 0u) { xcd_barrier_complete(bar, b.x, nloc, nx); b.st[0] = nloc; b.st[1] = nx; }
.LBB0_685:
	s_cmp_lt_u32 s89, 8
	s_cbranch_scc1 .LBB0_739
	s_waitcnt vmcnt(0)
	s_waitcnt lgkmcnt(0)
	s_barrier
	s_mov_b64 s[0:1], exec
	v_readlane_b32 s2, v254, 8
	v_readlane_b32 s3, v254, 9
	s_and_b64 s[2:3], s[0:1], s[2:3]
	s_mov_b64 exec, s[2:3]
	s_cbranch_execz .LBB0_738
	v_readlane_b32 s8, v254, 48
	s_mul_i32 s9, s97, s96
	s_mul_i32 s9, s9, s90
	s_cmp_lg_u32 s8, 0
	s_cbranch_scc1 .Lmy_sm5_have
	s_mov_b64 exec, 0xffff
	v_lshlrev_b32_e32 v0, 8, v208
	v_add_u32_e32 v0, 0x400, v0
	s_mov_b32 s5, 0

; __device__ __forceinline__ unsigned pk2(float lo, float hi) { return pg8::cvt_pk_bf16(lo, hi); }
; __device__ __forceinline__ void prepR_phase(const Params& P, int wid, int G, int NGW, int lane) {
;     ...
;         for (int ks = 0; ks < 8; ++ks) {
;             const int col = 32 * ks + 8 * fq; float p[8], pp[8]; ld8(PX + (size_t)row * 256 + col, true, p); ld8(PX + (size_t)(prow < 0 ? 0 : prow) * 256 + col, prow >= 0, pp);
;             const f32x4 m0 = *(const f32x4*)(mu + 1536 + col), m1 = *(const f32x4*)(mu + 1536 + col + 4); float x[8];
; #pragma unroll
;             for (int e = 0; e < 8; ++e) { const float m = e < 4 ? m0[e & 3] : m1[e & 3]; x[e] = p[e] + (pp[e] - p[e]) * m; }
;             if (ks < 2) {
; #pragma unroll
;                 for (int e = 0; e < 8; ++e) { const float t = __expf(-2.0f * __builtin_fabsf(x[e])); const float th = (1.0f - t) * __builtin_amdgcn_rcpf(1.0f + t); x[e] = x[e] < 0.f ? -th : th; }
;             } else if (ks >= 4) {
; #pragma unroll
;                 for (int e = 0; e < 8; ++e) x[e] = __builtin_amdgcn_rcpf(1.0f + __expf(-x[e]));
;             }
;             const u32x4 w = (u32x4){pk2(x[0], x[1]), pk2(x[2], x[3]), pk2(x[4], x[5]), pk2(x[6], x[7])};
;             const bf16x8 f = __builtin_bit_cast(bf16x8, w);
;             if (ks < 2) xwf[ks] = f; else if (ks < 4) xaf[ks - 2] = f; else xgf[ks - 4] = f;
.LBB0_763:
	s_or_b64 exec, exec, s[0:1]
	s_waitcnt vmcnt(0)
	v_lshlrev_b32_e32 v122, 16, v112
	v_and_b32_e32 v112, 0xffff0000, v112
	v_lshlrev_b32_e32 v126, 16, v108
	v_and_b32_e32 v108, 0xffff0000, v108
	v_lshlrev_b32_e32 v123, 16, v113
	v_lshlrev_b32_e32 v127, 16, v109
	v_sub_f32_e32 v108, v108, v112
	v_and_b32_e32 v113, 0xffff0000, v113
	v_and_b32_e32 v109, 0xffff0000, v109
	v_fmac_f32_e32 v112, v117, v108
	v_sub_f32_e32 v108, v127, v123
	v_lshlrev_b32_e32 v124, 16, v114
	v_lshlrev_b32_e32 v128, 16, v110
	v_fmac_f32_e32 v123, v118, v108
	v_sub_f32_e32 v108, v109, v113
	v_lshlrev_b32_e32 v125, 16, v115
	v_lshlrev_b32_e32 v129, 16, v111
	v_fmac_f32_e32 v113, v119, v108
	v_sub_f32_e32 v108, v128, v124
	v_and_b32_e32 v115, 0xffff0000, v115
	v_and_b32_e32 v111, 0xffff0000, v111
	v_fmac_f32_e32 v124, v0, v108
	v_sub_f32_e32 v108, v129, v125
	v_fmac_f32_e32 v125, v2, v108
	v_sub_f32_e32 v2, v111, v115
	v_fmac_f32_e32 v115, v3, v2
	v_mul_f32_e32 v2, 0xbfb8aa3b, v115
	v_exp_f32_e32 v2, v2
	v_mul_f32_e32 v3, 0xbfb8aa3b, v125
	v_and_b32_e32 v114, 0xffff0000, v114
	v_and_b32_e32 v110, 0xffff0000, v110
	v_exp_f32_e32 v3, v3
	v_sub_f32_e32 v0, v110, v114
	v_fmac_f32_e32 v114, v1, v0
	v_add_f32_e32 v0, 1.0, v2
	v_mul_f32_e32 v1, 0xbfb8aa3b, v114
	v_rcp_f32_e32 v108, v0
	v_add_f32_e32 v0, 1.0, v3
	v_exp_f32_e32 v1, v1
	v_mul_f32_e32 v2, 0xbfb8aa3b, v124
	v_mul_f32_e32 v3, 0xbfb8aa3b, v113
	v_exp_f32_e32 v2, v2
	v_exp_f32_e32 v3, v3
	v_add_f32_e32 v1, 1.0, v1
	v_rcp_f32_e32 v109, v1
	v_add_f32_e32 v1, 1.0, v2
	v_add_f32_e32 v2, 1.0, v3
	v_mul_f32_e32 v3, 0xbfb8aa3b, v123
	v_exp_f32_e32 v3, v3
	v_rcp_f32_e32 v2, v2
	v_mul_f32_e32 v110, 0xbfb8aa3b, v112
	v_rcp_f32_e32 v112, v1
	v_add_f32_e32 v3, 1.0, v3
	v_rcp_f32_e32 v3, v3
	v_rcp_f32_e32 v113, v0
	v_sub_f32_e32 v126, v126, v122
	v_fmac_f32_e32 v122, v116, v126
	v_cvt_pk_bf16_f32 v1, v3, v2
	v_cvt_pk_bf16_f32 v2, v112, v109
	v_lshlrev_b32_e32 v112, 16, v96
	v_and_b32_e32 v96, 0xffff0000, v96
	v_lshlrev_b32_e32 v116, 16, v4
	v_and_b32_e32 v4, 0xffff0000, v4
	v_cvt_pk_bf16_f32 v3, v113, v108
	v_lshlrev_b32_e32 v113, 16, v97
	v_lshlrev_b32_e32 v117, 16, v5
	v_sub_f32_e32 v4, v4, v96
	v_and_b32_e32 v97, 0xffff0000, v97
	v_lshlrev_b32_e32 v115, 16, v99
	v_and_b32_e32 v5, 0xffff0000, v5
	v_lshlrev_b32_e32 v119, 16, v7
	v_fmac_f32_e32 v96, v101, v4
	v_sub_f32_e32 v4, v117, v113
	v_and_b32_e32 v99, 0xffff0000, v99
	v_and_b32_e32 v7, 0xffff0000, v7
	v_fmac_f32_e32 v113, v102, v4
	v_sub_f32_e32 v4, v5, v97
	v_sub_f32_e32 v5, v119, v115
	v_fmac_f32_e32 v115, v94, v5
	v_sub_f32_e32 v5, v7, v99
	v_lshlrev_b32_e32 v114, 16, v98
	v_lshlrev_b32_e32 v118, 16, v6
	v_fmac_f32_e32 v99, v95, v5
	v_and_b32_e32 v98, 0xffff0000, v98
	v_and_b32_e32 v6, 0xffff0000, v6
	v_fmac_f32_e32 v97, v103, v4
	v_sub_f32_e32 v4, v118, v114
	v_mul_f32_e32 v5, 0xbfb8aa3b, v99
	v_fmac_f32_e32 v114, v92, v4
	v_sub_f32_e32 v4, v6, v98
	v_exp_f32_e32 v5, v5
	v_mul_f32_e32 v6, 0xbfb8aa3b, v115
	v_exp_f32_e32 v6, v6
	v_fmac_f32_e32 v98, v93, v4
	v_add_f32_e32 v4, 1.0, v5
	v_mul_f32_e32 v5, 0xbfb8aa3b, v98
	v_rcp_f32_e32 v7, v4
	v_add_f32_e32 v4, 1.0, v6
	v_exp_f32_e32 v5, v5
	v_mul_f32_e32 v6, 0xbfb8aa3b, v114
	v_mul_f32_e32 v92, 0xbfb8aa3b, v97
	v_exp_f32_e32 v6, v6
	v_exp_f32_e32 v92, v92
	v_add_f32_e32 v5, 1.0, v5
	v_rcp_f32_e32 v93, v5
	v_add_f32_e32 v5, 1.0, v6
	v_add_f32_e32 v6, 1.0, v92
	v_mul_f32_e32 v92, 0xbfb8aa3b, v113
	v_sub_f32_e32 v116, v116, v112
	v_exp_f32_e32 v92, v92
	v_fmac_f32_e32 v112, v100, v116
	v_mul_f32_e32 v94, 0xbfb8aa3b, v96
	v_mul_f32_e32 v95, 0xbfb8aa3b, v112
	v_exp_f32_e32 v94, v94
	v_exp_f32_e32 v95, v95
	v_add_f32_e32 v92, 1.0, v92
	v_rcp_f32_e32 v6, v6
	v_rcp_f32_e32 v92, v92
	v_rcp_f32_e32 v96, v5
	v_rcp_f32_e32 v97, v4
	v_add_f32_e32 v94, 1.0, v94
	v_add_f32_e32 v95, 1.0, v95
	v_rcp_f32_e32 v94, v94
	v_rcp_f32_e32 v95, v95
	v_cvt_pk_bf16_f32 v5, v92, v6
	v_cvt_pk_bf16_f32 v6, v96, v93
	v_lshlrev_b32_e32 v92, 16, v84
	v_and_b32_e32 v84, 0xffff0000, v84
	v_lshlrev_b32_e32 v96, 16, v80
	v_and_b32_e32 v80, 0xffff0000, v80
	v_cvt_pk_bf16_f32 v7, v97, v7
	v_lshlrev_b32_e32 v93, 16, v85
	v_lshlrev_b32_e32 v97, 16, v81
	v_sub_f32_e32 v80, v80, v84
	v_and_b32_e32 v85, 0xffff0000, v85
	v_and_b32_e32 v81, 0xffff0000, v81
	v_fmac_f32_e32 v84, v89, v80
	v_sub_f32_e32 v80, v97, v93
	v_cvt_pk_bf16_f32 v4, v95, v94
	v_lshlrev_b32_e32 v94, 16, v86
	v_lshlrev_b32_e32 v98, 16, v82
	v_fmac_f32_e32 v93, v90, v80
	v_sub_f32_e32 v80, v81, v85
	v_lshlrev_b32_e32 v95, 16, v87
	v_lshlrev_b32_e32 v99, 16, v83
	v_fmac_f32_e32 v85, v91, v80
	v_sub_f32_e32 v80, v98, v94
	v_and_b32_e32 v87, 0xffff0000, v87
	v_and_b32_e32 v83, 0xffff0000, v83
	v_fmac_f32_e32 v94, v8, v80
	v_sub_f32_e32 v80, v99, v95
	v_fmac_f32_e32 v95, v10, v80
	v_sub_f32_e32 v10, v83, v87
	v_fmac_f32_e32 v87, v11, v10
	v_mul_f32_e32 v10, 0xbfb8aa3b, v87
	v_exp_f32_e32 v10, v10
	v_mul_f32_e32 v11, 0xbfb8aa3b, v95
	v_and_b32_e32 v86, 0xffff0000, v86
	v_and_b32_e32 v82, 0xffff0000, v82
	v_exp_f32_e32 v11, v11
	v_sub_f32_e32 v8, v82, v86
	v_fmac_f32_e32 v86, v9, v8
	v_add_f32_e32 v8, 1.0, v10
	v_mul_f32_e32 v9, 0xbfb8aa3b, v86
	v_rcp_f32_e32 v80, v8
	v_add_f32_e32 v8, 1.0, v11
	v_exp_f32_e32 v9, v9
	v_mul_f32_e32 v10, 0xbfb8aa3b, v94
	v_mul_f32_e32 v11, 0xbfb8aa3b, v85
	v_exp_f32_e32 v10, v10
	v_exp_f32_e32 v11, v11
	v_add_f32_e32 v9, 1.0, v9
	v_sub_f32_e32 v96, v96, v92
	v_rcp_f32_e32 v81, v9
	v_add_f32_e32 v9, 1.0, v10
	v_add_f32_e32 v10, 1.0, v11
	v_mul_f32_e32 v11, 0xbfb8aa3b, v93
	v_fmac_f32_e32 v92, v88, v96
	v_exp_f32_e32 v11, v11
	v_mul_f32_e32 v82, 0xbfb8aa3b, v84
	v_mul_f32_e32 v83, 0xbfb8aa3b, v92
	v_exp_f32_e32 v82, v82
	v_exp_f32_e32 v83, v83
	v_add_f32_e32 v11, 1.0, v11
; __device__ __forceinline__ unsigned pk2(float lo, float hi) { return pg8::cvt_pk_bf16(lo, hi); }
; __device__ __forceinline__ void prepR_phase(const Params& P, int wid, int G, int NGW, int lane) {
;     ...
;         for (int ks = 0; ks < 8; ++ks) {
;             const int col = 32 * ks + 8 * fq; float p[8], pp[8]; ld8(PX + (size_t)row * 256 + col, true, p); ld8(PX + (size_t)(prow < 0 ? 0 : prow) * 256 + col, prow >= 0, pp);
;             const f32x4 m0 = *(const f32x4*)(mu + 1536 + col), m1 = *(const f32x4*)(mu + 1536 + col + 4); float x[8];
; #pragma unroll
;             for (int e = 0; e < 8; ++e) { const float m = e < 4 ? m0[e & 3] : m1[e & 3]; x[e] = p[e] + (pp[e] - p[e]) * m; }
;             if (ks < 2) {
; #pragma unroll
;                 for (int e = 0; e < 8; ++e) { const float t = __expf(-2.0f * __builtin_fabsf(x[e])); const float th = (1.0f - t) * __builtin_amdgcn_rcpf(1.0f + t); x[e] = x[e] < 0.f ? -th : th; }
;             } else if (ks >= 4) {
; #pragma unroll
;                 for (int e = 0; e < 8; ++e) x[e] = __builtin_amdgcn_rcpf(1.0f + __expf(-x[e]));
;             }
;             const u32x4 w = (u32x4){pk2(x[0], x[1]), pk2(x[2], x[3]), pk2(x[4], x[5]), pk2(x[6], x[7])};
;             const bf16x8 f = __builtin_bit_cast(bf16x8, w);
;             if (ks < 2) xwf[ks] = f; else if (ks < 4) xaf[ks - 2] = f; else xgf[ks - 4] = f;
	v_rcp_f32_e32 v10, v10
	v_rcp_f32_e32 v11, v11
	v_rcp_f32_e32 v84, v9
	v_rcp_f32_e32 v85, v8
	v_add_f32_e32 v82, 1.0, v82
	v_add_f32_e32 v83, 1.0, v83
	v_rcp_f32_e32 v82, v82
	v_rcp_f32_e32 v83, v83
	v_cvt_pk_bf16_f32 v9, v11, v10
	v_cvt_pk_bf16_f32 v10, v84, v81
	v_cvt_pk_bf16_f32 v11, v85, v80
	v_lshlrev_b32_e32 v80, 16, v72
	v_and_b32_e32 v81, 0xffff0000, v72
	v_lshlrev_b32_e32 v72, 16, v73
	v_and_b32_e32 v73, 0xffff0000, v73
	v_lshlrev_b32_e32 v84, 16, v12
	v_and_b32_e32 v85, 0xffff0000, v12
	v_lshlrev_b32_e32 v12, 16, v13
	v_and_b32_e32 v13, 0xffff0000, v13
	v_pk_add_f32 v[12:13], v[12:13], v[72:73] neg_lo:[0,1] neg_hi:[0,1]
	v_cvt_pk_bf16_f32 v8, v83, v82
	v_lshlrev_b32_e32 v82, 16, v74
	v_and_b32_e32 v83, 0xffff0000, v74
	v_pk_fma_f32 v[72:73], v[78:79], v[12:13], v[72:73]
	v_lshlrev_b32_e32 v12, 16, v14
	v_and_b32_e32 v13, 0xffff0000, v14
	v_pk_add_f32 v[12:13], v[12:13], v[82:83] neg_lo:[0,1] neg_hi:[0,1]
	v_lshlrev_b32_e32 v74, 16, v75
	v_and_b32_e32 v75, 0xffff0000, v75
	v_pk_fma_f32 v[68:69], v[68:69], v[12:13], v[82:83]
	v_lshlrev_b32_e32 v12, 16, v15
	v_and_b32_e32 v13, 0xffff0000, v15
	v_pk_add_f32 v[12:13], v[12:13], v[74:75] neg_lo:[0,1] neg_hi:[0,1]
	v_cvt_pk_bf16_f32 v14, v68, v69
	v_pk_fma_f32 v[70:71], v[70:71], v[12:13], v[74:75]
	v_cvt_pk_bf16_f32 v13, v72, v73
	v_lshlrev_b32_e32 v68, 16, v60
	v_and_b32_e32 v69, 0xffff0000, v60
	v_lshlrev_b32_e32 v60, 16, v61
	v_and_b32_e32 v61, 0xffff0000, v61
	v_lshlrev_b32_e32 v72, 16, v16
	v_and_b32_e32 v73, 0xffff0000, v16
	v_lshlrev_b32_e32 v16, 16, v17
	v_and_b32_e32 v17, 0xffff0000, v17
	v_pk_add_f32 v[16:17], v[16:17], v[60:61] neg_lo:[0,1] neg_hi:[0,1]
	v_cvt_pk_bf16_f32 v15, v70, v71
	v_lshlrev_b32_e32 v70, 16, v62
	v_and_b32_e32 v71, 0xffff0000, v62
	v_pk_fma_f32 v[60:61], v[66:67], v[16:17], v[60:61]
	v_lshlrev_b32_e32 v16, 16, v18
	v_and_b32_e32 v17, 0xffff0000, v18
	v_pk_add_f32 v[16:17], v[16:17], v[70:71] neg_lo:[0,1] neg_hi:[0,1]
	v_lshlrev_b32_e32 v62, 16, v63
	v_and_b32_e32 v63, 0xffff0000, v63
	v_pk_fma_f32 v[56:57], v[56:57], v[16:17], v[70:71]
	v_lshlrev_b32_e32 v16, 16, v19
	v_and_b32_e32 v17, 0xffff0000, v19
	v_pk_add_f32 v[16:17], v[16:17], v[62:63] neg_lo:[0,1] neg_hi:[0,1]
	v_cvt_pk_bf16_f32 v18, v56, v57
	v_pk_fma_f32 v[58:59], v[58:59], v[16:17], v[62:63]
	v_cvt_pk_bf16_f32 v17, v60, v61
	v_cvt_pk_bf16_f32 v19, v58, v59
	v_lshlrev_b32_e32 v58, 16, v51
	v_and_b32_e32 v59, 0xffff0000, v51
	v_lshlrev_b32_e32 v60, 16, v23
	v_and_b32_e32 v61, 0xffff0000, v23
	v_pk_add_f32 v[60:61], v[60:61], v[58:59] neg_lo:[0,1] neg_hi:[0,1]
	v_lshlrev_b32_e32 v62, 16, v50
	v_pk_fma_f32 v[54:55], v[54:55], v[60:61], v[58:59]
	v_and_b32_e32 v63, 0xffff0000, v50
	v_mul_f32_e64 v23, |v55|, -2.0
	v_mul_f32_e32 v23, 0x3fb8aa3b, v23
	v_exp_f32_e32 v59, v23
	v_mul_f32_e64 v23, |v54|, -2.0
	v_mul_f32_e32 v23, 0x3fb8aa3b, v23
	v_exp_f32_e32 v58, v23
	v_add_f32_e32 v23, 1.0, v59
	v_rcp_f32_e32 v61, v23
	v_cmp_gt_f32_e64 s[0:1], 0, v55
	v_add_f32_e32 v23, 1.0, v58
	v_pk_add_f32 v[50:51], v[58:59], 1.0 op_sel_hi:[1,0] neg_lo:[1,0] neg_hi:[1,0]
	v_lshlrev_b32_e32 v58, 16, v22
	v_and_b32_e32 v59, 0xffff0000, v22
	v_rcp_f32_e32 v60, v23
	v_pk_add_f32 v[22:23], v[58:59], v[62:63] neg_lo:[0,1] neg_hi:[0,1]
	v_lshlrev_b32_e32 v56, 16, v48
	v_pk_fma_f32 v[22:23], v[52:53], v[22:23], v[62:63]
	v_pk_mul_f32 v[50:51], v[50:51], v[60:61]
	v_mul_f32_e64 v52, |v23|, -2.0
	v_mul_f32_e32 v52, 0x3fb8aa3b, v52
	v_exp_f32_e32 v53, v52
	v_mul_f32_e64 v52, |v22|, -2.0
	v_mul_f32_e32 v52, 0x3fb8aa3b, v52
	v_exp_f32_e32 v52, v52
	v_cndmask_b32_e64 v55, v51, -v51, s[0:1]
	v_add_f32_e32 v51, 1.0, v53
	v_rcp_f32_e32 v59, v51
	v_add_f32_e32 v51, 1.0, v52
	v_cmp_gt_f32_e64 s[0:1], 0, v54
	v_and_b32_e32 v57, 0xffff0000, v48
	v_lshlrev_b32_e32 v48, 16, v49
	v_and_b32_e32 v49, 0xffff0000, v49
	v_rcp_f32_e32 v58, v51
	v_cndmask_b32_e64 v54, v50, -v50, s[0:1]
	v_pk_add_f32 v[50:51], v[52:53], 1.0 op_sel_hi:[1,0] neg_lo:[1,0] neg_hi:[1,0]
	v_lshlrev_b32_e32 v52, 16, v21
	v_and_b32_e32 v53, 0xffff0000, v21
	v_pk_add_f32 v[52:53], v[52:53], v[48:49] neg_lo:[0,1] neg_hi:[0,1]
	v_pk_mul_f32 v[50:51], v[50:51], v[58:59]
	v_pk_fma_f32 v[46:47], v[46:47], v[52:53], v[48:49]
	v_cmp_gt_f32_e64 s[0:1], 0, v23
	v_mul_f32_e64 v21, |v47|, -2.0
	v_mul_f32_e32 v21, 0x3fb8aa3b, v21
	v_exp_f32_e32 v49, v21
	v_mul_f32_e64 v21, |v46|, -2.0
	v_mul_f32_e32 v21, 0x3fb8aa3b, v21
	v_exp_f32_e32 v48, v21
	v_add_f32_e32 v21, 1.0, v49
	v_cndmask_b32_e64 v51, v51, -v51, s[0:1]
	v_rcp_f32_e32 v53, v21
	v_add_f32_e32 v21, 1.0, v48
	v_cmp_gt_f32_e64 s[0:1], 0, v22
	v_pk_add_f32 v[22:23], v[48:49], 1.0 op_sel_hi:[1,0] neg_lo:[1,0] neg_hi:[1,0]
	v_lshlrev_b32_e32 v48, 16, v20
	v_and_b32_e32 v49, 0xffff0000, v20
	v_rcp_f32_e32 v52, v21
	v_pk_add_f32 v[20:21], v[48:49], v[56:57] neg_lo:[0,1] neg_hi:[0,1]
	v_cndmask_b32_e64 v50, v50, -v50, s[0:1]
	v_pk_fma_f32 v[20:21], v[44:45], v[20:21], v[56:57]
	v_pk_mul_f32 v[22:23], v[22:23], v[52:53]
	v_mul_f32_e64 v44, |v21|, -2.0
	v_mul_f32_e32 v44, 0x3fb8aa3b, v44
	v_exp_f32_e32 v45, v44
	v_mul_f32_e64 v44, |v20|, -2.0
	v_mul_f32_e32 v44, 0x3fb8aa3b, v44
	v_exp_f32_e32 v44, v44
	v_cmp_gt_f32_e64 s[0:1], 0, v47
	v_mul_f32_e32 v111, 0xbfb8aa3b, v122
	v_exp_f32_e32 v110, v110
	v_cndmask_b32_e64 v47, v23, -v23, s[0:1]
	v_add_f32_e32 v23, 1.0, v45
	v_rcp_f32_e32 v49, v23
	v_add_f32_e32 v23, 1.0, v44
	v_rcp_f32_e32 v48, v23
	v_cmp_gt_f32_e64 s[0:1], 0, v46
	v_exp_f32_e32 v111, v111
	v_add_f32_e32 v110, 1.0, v110
	v_cndmask_b32_e64 v46, v22, -v22, s[0:1]
	v_pk_add_f32 v[22:23], v[44:45], 1.0 op_sel_hi:[1,0] neg_lo:[1,0] neg_hi:[1,0]
	v_cmp_gt_f32_e64 s[0:1], 0, v21
	v_pk_mul_f32 v[22:23], v[22:23], v[48:49]
; __device__ __forceinline__ unsigned pk2(float lo, float hi) { return pg8::cvt_pk_bf16(lo, hi); }
; __device__ __forceinline__ void prepR_phase(const Params& P, int wid, int G, int NGW, int lane) {
;     ...
;         for (int ks = 0; ks < 8; ++ks) {
;             const int col = 32 * ks + 8 * fq; float p[8], pp[8]; ld8(PX + (size_t)row * 256 + col, true, p); ld8(PX + (size_t)(prow < 0 ? 0 : prow) * 256 + col, prow >= 0, pp);
;             const f32x4 m0 = *(const f32x4*)(mu + 1536 + col), m1 = *(const f32x4*)(mu + 1536 + col + 4); float x[8];
; #pragma unroll
;             for (int e = 0; e < 8; ++e) { const float m = e < 4 ? m0[e & 3] : m1[e & 3]; x[e] = p[e] + (pp[e] - p[e]) * m; }
;             if (ks < 2) {
; #pragma unroll
;                 for (int e = 0; e < 8; ++e) { const float t = __expf(-2.0f * __builtin_fabsf(x[e])); const float th = (1.0f - t) * __builtin_amdgcn_rcpf(1.0f + t); x[e] = x[e] < 0.f ? -th : th; }
;             } else if (ks >= 4) {
; #pragma unroll
;                 for (int e = 0; e < 8; ++e) x[e] = __builtin_amdgcn_rcpf(1.0f + __expf(-x[e]));
;             }
;             const u32x4 w = (u32x4){pk2(x[0], x[1]), pk2(x[2], x[3]), pk2(x[4], x[5]), pk2(x[6], x[7])};
;             const bf16x8 f = __builtin_bit_cast(bf16x8, w);
;             if (ks < 2) xwf[ks] = f; else if (ks < 4) xaf[ks - 2] = f; else xgf[ks - 4] = f;
	v_lshlrev_b32_e32 v48, 16, v35
	v_cndmask_b32_e64 v21, v23, -v23, s[0:1]
	v_cmp_gt_f32_e64 s[0:1], 0, v20
	v_and_b32_e32 v49, 0xffff0000, v35
	v_lshlrev_b32_e32 v44, 16, v32
	v_cndmask_b32_e64 v20, v22, -v22, s[0:1]
	v_cvt_pk_bf16_f32 v22, v50, v51
	v_lshlrev_b32_e32 v50, 16, v27
	v_and_b32_e32 v51, 0xffff0000, v27
	v_pk_add_f32 v[50:51], v[50:51], v[48:49] neg_lo:[0,1] neg_hi:[0,1]
	v_cvt_pk_bf16_f32 v20, v20, v21
	v_pk_fma_f32 v[48:49], v[42:43], v[50:51], v[48:49]
	v_cvt_pk_bf16_f32 v21, v46, v47
	v_mul_f32_e64 v27, |v49|, -2.0
	v_mul_f32_e32 v27, 0x3fb8aa3b, v27
	v_exp_f32_e32 v43, v27
	v_mul_f32_e64 v27, |v48|, -2.0
	v_mul_f32_e32 v27, 0x3fb8aa3b, v27
	v_exp_f32_e32 v42, v27
	v_add_f32_e32 v27, 1.0, v43
	v_lshlrev_b32_e32 v46, 16, v33
	v_and_b32_e32 v47, 0xffff0000, v33
	v_rcp_f32_e32 v33, v27
	v_add_f32_e32 v27, 1.0, v42
	v_and_b32_e32 v45, 0xffff0000, v32
	v_rcp_f32_e32 v32, v27
	v_lshlrev_b32_e32 v50, 16, v34
	v_and_b32_e32 v51, 0xffff0000, v34
	v_pk_add_f32 v[34:35], v[42:43], 1.0 op_sel_hi:[1,0] neg_lo:[1,0] neg_hi:[1,0]
	v_cmp_gt_f32_e64 s[0:1], 0, v49
	v_pk_mul_f32 v[52:53], v[34:35], v[32:33]
	v_lshlrev_b32_e32 v32, 16, v26
	v_and_b32_e32 v33, 0xffff0000, v26
	v_pk_add_f32 v[26:27], v[32:33], v[50:51] neg_lo:[0,1] neg_hi:[0,1]
	v_cvt_pk_bf16_f32 v23, v54, v55
	v_pk_fma_f32 v[26:27], v[40:41], v[26:27], v[50:51]
	global_load_dwordx4 v[32:35], v[164:165], off offset:16
	global_load_dwordx4 v[40:43], v[164:165], off
	v_mul_f32_e64 v50, |v27|, -2.0
	v_mul_f32_e32 v50, 0x3fb8aa3b, v50
	v_exp_f32_e32 v51, v50
	v_mul_f32_e64 v50, |v26|, -2.0
	v_mul_f32_e32 v50, 0x3fb8aa3b, v50
	v_exp_f32_e32 v50, v50
	v_add_f32_e32 v49, 1.0, v51
	v_rcp_f32_e32 v55, v49
	v_cndmask_b32_e64 v53, v53, -v53, s[0:1]
	v_add_f32_e32 v49, 1.0, v50
	v_rcp_f32_e32 v54, v49
	v_cmp_gt_f32_e64 s[0:1], 0, v48
	v_pk_add_f32 v[48:49], v[50:51], 1.0 op_sel_hi:[1,0] neg_lo:[1,0] neg_hi:[1,0]
	v_lshlrev_b32_e32 v50, 16, v25
	v_and_b32_e32 v51, 0xffff0000, v25
	v_pk_add_f32 v[50:51], v[50:51], v[46:47] neg_lo:[0,1] neg_hi:[0,1]
	v_cndmask_b32_e64 v52, v52, -v52, s[0:1]
	v_pk_fma_f32 v[30:31], v[30:31], v[50:51], v[46:47]
	v_pk_mul_f32 v[48:49], v[48:49], v[54:55]
	v_mul_f32_e64 v25, |v31|, -2.0
	v_mul_f32_e32 v25, 0x3fb8aa3b, v25
	v_exp_f32_e32 v47, v25
	v_mul_f32_e64 v25, |v30|, -2.0
	v_mul_f32_e32 v25, 0x3fb8aa3b, v25
	v_exp_f32_e32 v46, v25
	v_cmp_gt_f32_e64 s[0:1], 0, v27
	v_add_f32_e32 v25, 1.0, v47
	v_rcp_f32_e32 v51, v25
	v_cndmask_b32_e64 v49, v49, -v49, s[0:1]
	v_add_f32_e32 v25, 1.0, v46
	v_cmp_gt_f32_e64 s[0:1], 0, v26
	v_pk_add_f32 v[26:27], v[46:47], 1.0 op_sel_hi:[1,0] neg_lo:[1,0] neg_hi:[1,0]
	v_lshlrev_b32_e32 v46, 16, v24
	v_and_b32_e32 v47, 0xffff0000, v24
	v_rcp_f32_e32 v50, v25
	v_pk_add_f32 v[24:25], v[46:47], v[44:45] neg_lo:[0,1] neg_hi:[0,1]
	v_cndmask_b32_e64 v48, v48, -v48, s[0:1]
	v_pk_fma_f32 v[24:25], v[28:29], v[24:25], v[44:45]
	v_pk_mul_f32 v[26:27], v[26:27], v[50:51]
	v_mul_f32_e64 v28, |v25|, -2.0
	v_mul_f32_e32 v28, 0x3fb8aa3b, v28
	v_exp_f32_e32 v29, v28
	v_mul_f32_e64 v28, |v24|, -2.0
	v_mul_f32_e32 v28, 0x3fb8aa3b, v28
	v_exp_f32_e32 v28, v28
	v_cmp_gt_f32_e64 s[0:1], 0, v31
	v_add_f32_e32 v111, 1.0, v111
	v_rcp_f32_e32 v110, v110
	v_cndmask_b32_e64 v31, v27, -v27, s[0:1]
	v_add_f32_e32 v27, 1.0, v29
	v_rcp_f32_e32 v45, v27
	v_add_f32_e32 v27, 1.0, v28
	v_rcp_f32_e32 v44, v27
	v_cmp_gt_f32_e64 s[0:1], 0, v30
	v_rcp_f32_e32 v111, v111
	v_lshlrev_b32_e32 v108, 16, v104
	v_cndmask_b32_e64 v30, v26, -v26, s[0:1]
	v_pk_add_f32 v[26:27], v[28:29], 1.0 op_sel_hi:[1,0] neg_lo:[1,0] neg_hi:[1,0]
	v_cmp_gt_f32_e64 s[0:1], 0, v25
	v_pk_mul_f32 v[26:27], v[26:27], v[44:45]
	v_lshlrev_b32_e32 v28, 16, v36
	v_cndmask_b32_e64 v25, v27, -v27, s[0:1]
	v_cmp_gt_f32_e64 s[0:1], 0, v24
	v_cvt_pk_bf16_f32 v0, v111, v110
	v_and_b32_e32 v104, 0xffff0000, v104
	v_cndmask_b32_e64 v24, v26, -v26, s[0:1]
	v_lshlrev_b32_e32 v111, 16, v107
	v_cvt_pk_bf16_f32 v24, v24, v25
	v_cvt_pk_bf16_f32 v25, v30, v31
	v_and_b32_e32 v29, 0xffff0000, v36
	v_lshlrev_b32_e32 v30, 16, v37
	v_and_b32_e32 v31, 0xffff0000, v37
	v_lshlrev_b32_e32 v36, 16, v38
	v_and_b32_e32 v37, 0xffff0000, v38
	v_lshlrev_b32_e32 v38, 16, v39
	v_sub_f32_e32 v28, v28, v108
	v_and_b32_e32 v107, 0xffff0000, v107
	v_and_b32_e32 v39, 0xffff0000, v39
	v_lshlrev_b32_e32 v109, 16, v105
	s_waitcnt vmcnt(0)
; __device__ __forceinline__ unsigned pk2(float lo, float hi) { return pg8::cvt_pk_bf16(lo, hi); }
; __device__ __forceinline__ void prepR_phase(const Params& P, int wid, int G, int NGW, int lane) {
;     ...
;         const bool mt = it >= (MMAIN / 16) * 2; const int h0 = mt ? it - (MMAIN / 16) * 2 : 4 * (it & 1), nh = mt ? 1 : 4; const int row_raw = (mt ? MMAIN : 16 * (it >> 1)) + fr; const bool valid = row_raw < MVALID; const int row = valid ? row_raw : 0;
;         const int prow = (row >= MMAIN) ? (row == MMAIN ? -1 : row - 1) : ((row & (SEQ - 1)) == 0 ? MVALID - 1 : row - 1);
;         bf16x8 xwf[2], xaf[2], xgf[4];
; #pragma unroll
;         for (int ks = 0; ks < 8; ++ks) {
;             const int col = 32 * ks + 8 * fq; float p[8], pp[8]; ld8(PX + (size_t)row * 256 + col, true, p); ld8(PX + (size_t)(prow < 0 ? 0 : prow) * 256 + col, prow >= 0, pp);
;             const f32x4 m0 = *(const f32x4*)(mu + 1536 + col), m1 = *(const f32x4*)(mu + 1536 + col + 4); float x[8];
; #pragma unroll
;             for (int e = 0; e < 8; ++e) { const float m = e < 4 ? m0[e & 3] : m1[e & 3]; x[e] = p[e] + (pp[e] - p[e]) * m; }
;             if (ks < 2) {
; #pragma unroll
;                 for (int e = 0; e < 8; ++e) { const float t = __expf(-2.0f * __builtin_fabsf(x[e])); const float th = (1.0f - t) * __builtin_amdgcn_rcpf(1.0f + t); x[e] = x[e] < 0.f ? -th : th; }
;             } else if (ks >= 4) {
; #pragma unroll
;                 for (int e = 0; e < 8; ++e) x[e] = __builtin_amdgcn_rcpf(1.0f + __expf(-x[e]));
;             }
;             const u32x4 w = (u32x4){pk2(x[0], x[1]), pk2(x[2], x[3]), pk2(x[4], x[5]), pk2(x[6], x[7])};
;             const bf16x8 f = __builtin_bit_cast(bf16x8, w);
;             if (ks < 2) xwf[ks] = f; else if (ks < 4) xaf[ks - 2] = f; else xgf[ks - 4] = f;
;         }
; #pragma unroll 1
;         for (int h = h0; h < h0 + nh; ++h) {
	v_fmac_f32_e32 v108, v40, v28
	v_sub_f32_e32 v28, v29, v104
	v_sub_f32_e32 v29, v38, v111
	v_fmac_f32_e32 v111, v34, v29
	v_sub_f32_e32 v29, v39, v107
	v_fmac_f32_e32 v107, v35, v29
	v_and_b32_e32 v105, 0xffff0000, v105
	v_fmac_f32_e32 v104, v41, v28
	v_sub_f32_e32 v28, v30, v109
	v_mul_f32_e32 v29, 0xbfb8aa3b, v107
	v_lshlrev_b32_e32 v110, 16, v106
	v_fmac_f32_e32 v109, v42, v28
	v_sub_f32_e32 v28, v31, v105
	v_exp_f32_e32 v29, v29
	v_mul_f32_e32 v30, 0xbfb8aa3b, v111
	v_and_b32_e32 v106, 0xffff0000, v106
	v_fmac_f32_e32 v105, v43, v28
	v_sub_f32_e32 v28, v36, v110
	v_exp_f32_e32 v30, v30
	v_fmac_f32_e32 v110, v32, v28
	v_sub_f32_e32 v28, v37, v106
	v_fmac_f32_e32 v106, v33, v28
	v_add_f32_e32 v28, 1.0, v29
	v_mul_f32_e32 v29, 0xbfb8aa3b, v106
	v_rcp_f32_e32 v31, v28
	v_add_f32_e32 v28, 1.0, v30
	v_exp_f32_e32 v29, v29
	v_mul_f32_e32 v30, 0xbfb8aa3b, v110
	v_mul_f32_e32 v32, 0xbfb8aa3b, v105
	v_exp_f32_e32 v30, v30
	v_exp_f32_e32 v32, v32
	v_add_f32_e32 v29, 1.0, v29
	v_rcp_f32_e32 v33, v29
	v_add_f32_e32 v29, 1.0, v30
	v_add_f32_e32 v30, 1.0, v32
	v_mul_f32_e32 v32, 0xbfb8aa3b, v109
	v_exp_f32_e32 v32, v32
	v_mul_f32_e32 v34, 0xbfb8aa3b, v104
	v_mul_f32_e32 v35, 0xbfb8aa3b, v108
	v_exp_f32_e32 v34, v34
	v_exp_f32_e32 v35, v35
	s_lshl_b32 s0, s30, 2
	v_add_f32_e32 v32, 1.0, v32
	s_add_i32 s28, s30, 0xfffff800
	s_and_b32 s98, s28, 1
	s_lshr_b32 s28, s28, 1
	s_lshl_b32 s98, s98, 2
	s_add_i32 s28, s28, s98
	s_and_b32 s29, s0, 4
	v_rcp_f32_e32 v30, v30
	v_rcp_f32_e32 v32, v32
	v_rcp_f32_e32 v36, v29
	s_and_b64 s[0:1], s[4:5], exec
	s_cselect_b32 s28, s28, s29
	v_add_f32_e32 v34, 1.0, v34
	v_add_f32_e32 v35, 1.0, v35
	s_cselect_b32 s0, 1, 4
	s_mov_b32 s101, s0
	v_rcp_f32_e32 v34, v34
	v_rcp_f32_e32 v35, v35
	v_rcp_f32_e32 v37, v28
	s_ashr_i32 s29, s28, 31
	v_cvt_pk_bf16_f32 v29, v32, v30
	v_cvt_pk_bf16_f32 v30, v36, v33
	s_add_i32 s56, s28, s0
	v_lshlrev_b64 v[32:33], 1, v[170:171]
	v_max_i32_e32 v142, 0, v142
	s_lshl_b64 s[0:1], s[28:29], 2
	v_pk_add_f32 v[84:85], v[84:85], v[80:81] neg_lo:[0,1] neg_hi:[0,1]
	v_pk_add_f32 v[72:73], v[72:73], v[68:69] neg_lo:[0,1] neg_hi:[0,1]
	v_lshl_add_u64 v[172:173], s[6:7], 0, v[32:33]
	v_lshl_add_u64 v[174:175], s[8:9], 0, v[32:33]
	v_lshl_add_u64 v[176:177], s[10:11], 0, v[32:33]
	v_lshlrev_b64 v[32:33], 10, v[142:143]
	s_add_u32 s0, s31, s0
	v_pk_fma_f32 v[76:77], v[76:77], v[84:85], v[80:81]
	v_pk_fma_f32 v[64:65], v[64:65], v[72:73], v[68:69]
	v_lshl_add_u64 v[178:179], s[6:7], 0, v[32:33]
	v_lshl_add_u64 v[180:181], s[8:9], 0, v[32:33]
	v_lshl_add_u64 v[182:183], s[10:11], 0, v[32:33]
	v_lshlrev_b64 v[32:33], 5, v[120:121]
	s_addc_u32 s1, s34, s1
	v_cvt_pk_bf16_f32 v12, v76, v77
	v_cvt_pk_bf16_f32 v16, v64, v65
	v_cvt_pk_bf16_f32 v26, v48, v49
	v_cvt_pk_bf16_f32 v27, v52, v53
	v_cvt_pk_bf16_f32 v28, v35, v34
	v_cvt_pk_bf16_f32 v31, v37, v31
	v_lshl_add_u64 v[184:185], s[0:1], 0, v[32:33]
	s_lshl_b32 s29, s28, 6
	s_cmp_eq_u32 s101, 1
	s_cbranch_scc1 .Lmy_lora_nobar
	s_waitcnt vmcnt(0)
	s_barrier

; __device__ __forceinline__ void xcd_barrier(const XcdBarrier& b) {
;     asm volatile("s_waitcnt vmcnt(0)" ::: "memory");
;     __syncthreads();
;     if (threadIdx.x == 0) {
;         unsigned* bar = b.bar;
;         __builtin_amdgcn_s_waitcnt(0);
;         unsigned nloc = b.st[0], nx = b.st[1];
;         if (nloc == 0u) { xcd_barrier_complete(bar, b.x, nloc, nx); b.st[0] = nloc; b.st[1] = nx; }
.LBB0_779:
	s_cmp_lt_u32 s89, 9
	s_cbranch_scc1 .LBB0_833
	s_waitcnt vmcnt(0)
	s_waitcnt vmcnt(0) lgkmcnt(0)
	s_barrier
	s_mov_b64 s[0:1], exec
	v_readlane_b32 s2, v254, 8
	v_readlane_b32 s3, v254, 9
	s_and_b64 s[2:3], s[0:1], s[2:3]
	s_mov_b64 exec, s[2:3]
	s_cbranch_execz .LBB0_832
	v_readlane_b32 s8, v254, 48
	s_mul_i32 s9, s97, s96
	s_mul_i32 s9, s9, s90
	s_cmp_lg_u32 s8, 0
	s_cbranch_scc1 .Lmy_sm6_have
	s_mov_b64 exec, 0xffff
	v_lshlrev_b32_e32 v0, 8, v208
	v_add_u32_e32 v0, 0x400, v0
	s_mov_b32 s5, 0

; __device__ __forceinline__ void xcd_barrier(const XcdBarrier& b) {
;     asm volatile("s_waitcnt vmcnt(0)" ::: "memory");
;     __syncthreads();
;     if (threadIdx.x == 0) {
;         unsigned* bar = b.bar;
;         __builtin_amdgcn_s_waitcnt(0);
;         unsigned nloc = b.st[0], nx = b.st[1];
;         if (nloc == 0u) { xcd_barrier_complete(bar, b.x, nloc, nx); b.st[0] = nloc; b.st[1] = nx; }
.LBB0_884:
	v_readlane_b32 s66, v254, 30
	s_cmp_lt_u32 s89, 10
	v_readlane_b32 s67, v254, 31
	v_readlane_b32 s65, v254, 29
	v_readlane_b32 s90, v254, 28
	v_readlane_b32 s91, v254, 27
	s_cbranch_scc1 .LBB0_938
	s_waitcnt vmcnt(0)
	s_waitcnt vmcnt(0) lgkmcnt(0)
	s_barrier
	s_mov_b64 s[0:1], exec
	v_readlane_b32 s2, v254, 8
	v_readlane_b32 s3, v254, 9
	s_and_b64 s[2:3], s[0:1], s[2:3]
	s_mov_b64 exec, s[2:3]
	s_cbranch_execz .LBB0_937
	v_readlane_b32 s8, v254, 48
	s_mul_i32 s9, s97, s96
	s_mul_i32 s9, s9, s90
	s_cmp_lg_u32 s8, 0
	s_cbranch_scc1 .Lmy_sm7_have
	s_mov_b64 exec, 0xffff
	v_lshlrev_b32_e32 v0, 8, v208
	v_add_u32_e32 v0, 0x400, v0
	s_mov_b32 s5, 0

; __device__ __forceinline__ void xcd_barrier(const XcdBarrier& b) {
;     asm volatile("s_waitcnt vmcnt(0)" ::: "memory");
;     __syncthreads();
;     if (threadIdx.x == 0) {
;         unsigned* bar = b.bar;
;         __builtin_amdgcn_s_waitcnt(0);
;         unsigned nloc = b.st[0], nx = b.st[1];
;         if (nloc == 0u) { xcd_barrier_complete(bar, b.x, nloc, nx); b.st[0] = nloc; b.st[1] = nx; }
.LBB0_942:
	s_or_b64 exec, exec, s[0:1]
	s_cmp_lt_u32 s89, 11
	s_cbranch_scc1 .LBB0_996
	s_waitcnt vmcnt(0)
	s_waitcnt vmcnt(0)
	s_barrier
	s_mov_b64 s[0:1], exec
	v_readlane_b32 s2, v254, 8
	v_readlane_b32 s3, v254, 9
	s_and_b64 s[2:3], s[0:1], s[2:3]
	s_mov_b64 exec, s[2:3]
	s_cbranch_execz .LBB0_995
	v_readlane_b32 s8, v254, 48
	s_mul_i32 s9, s97, s96
	s_mul_i32 s9, s9, s90
	s_cmp_lg_u32 s8, 0
	s_cbranch_scc1 .Lmy_sm8_have
	s_mov_b64 exec, 0xffff
	v_lshlrev_b32_e32 v0, 8, v208
	v_add_u32_e32 v0, 0x400, v0
	s_mov_b32 s5, 0

; __device__ __forceinline__ void xcd_barrier(const XcdBarrier& b) {
;     asm volatile("s_waitcnt vmcnt(0)" ::: "memory");
;     __syncthreads();
;     if (threadIdx.x == 0) {
;         unsigned* bar = b.bar;
;         __builtin_amdgcn_s_waitcnt(0);
;         unsigned nloc = b.st[0], nx = b.st[1];
;         if (nloc == 0u) { xcd_barrier_complete(bar, b.x, nloc, nx); b.st[0] = nloc; b.st[1] = nx; }
.LBB0_1040:
	s_waitcnt vmcnt(0)
	s_waitcnt vmcnt(0) lgkmcnt(0)
	s_barrier
	s_mov_b64 s[2:3], exec
	v_readlane_b32 s4, v254, 8
	v_readlane_b32 s5, v254, 9
	s_and_b64 s[4:5], s[2:3], s[4:5]
	s_mov_b64 exec, s[4:5]
	s_cbranch_execz .LBB0_1092
	v_readlane_b32 s8, v254, 48
	s_mul_i32 s9, s97, s96
	s_mul_i32 s9, s9, s90
	s_cmp_lg_u32 s8, 0
	s_cbranch_scc1 .Lmy_sm9_have
	s_mov_b64 exec, 0xffff
	v_lshlrev_b32_e32 v0, 8, v208
	v_add_u32_e32 v0, 0x400, v0
	s_mov_b32 s5, 0

; __device__ __forceinline__ unsigned xb_ld(unsigned* p)              { return __hip_atomic_load(p, __ATOMIC_RELAXED, __HIP_MEMORY_SCOPE_AGENT); }
; #define XB_SPIN(cond, bar) do { unsigned _sp = 0; while (cond) { __builtin_amdgcn_s_sleep(1); \
;     if ((++_sp & 255u) == 0u) { if (xb_ld(&(bar)[XB_TMO])) break; if (_sp > XB_SPIN_CAP) { atomicAdd(&(bar)[XB_TMO], 1u); break; } } } } while (0)
; __device__ __forceinline__ void xcd_barrier(const XcdBarrier& b) {
;     ...
;         } else {
;             XB_SPIN(xb_ld(&bar[XB_XGEN(b.x)]) == gen, bar);
;             __builtin_amdgcn_fence(__ATOMIC_ACQUIRE, "agent");
;             asm volatile("s_waitcnt vmcnt(0)" ::: "memory");
;         }
;     }
;     __syncthreads();
; }
.Lmy_sm9_done:
.LBB0_1092:
	s_or_b64 exec, exec, s[2:3]
	s_waitcnt lgkmcnt(0)
	s_barrier

; __device__ __forceinline__ void xcd_barrier(const XcdBarrier& b) {
;     asm volatile("s_waitcnt vmcnt(0)" ::: "memory");
;     __syncthreads();
;     if (threadIdx.x == 0) {
;         unsigned* bar = b.bar;
;         __builtin_amdgcn_s_waitcnt(0);
;         unsigned nloc = b.st[0], nx = b.st[1];
;         if (nloc == 0u) { xcd_barrier_complete(bar, b.x, nloc, nx); b.st[0] = nloc; b.st[1] = nx; }
.LBB0_1114:
	s_cmp_lt_u32 s89, 14
	s_cbranch_scc1 .LBB0_1168
	s_waitcnt vmcnt(0)
	s_waitcnt vmcnt(0) lgkmcnt(0)
	s_barrier
	s_mov_b64 s[0:1], exec
	v_readlane_b32 s2, v254, 8
	v_readlane_b32 s3, v254, 9
	s_and_b64 s[2:3], s[0:1], s[2:3]
	s_mov_b64 exec, s[2:3]
	s_cbranch_execz .LBB0_1167
	v_readlane_b32 s8, v254, 48
	s_mul_i32 s9, s97, s96
	s_mul_i32 s9, s9, s90
	s_cmp_lg_u32 s8, 0
	s_cbranch_scc1 .Lmy_sm10_have
	s_mov_b64 exec, 0xffff
	v_lshlrev_b32_e32 v0, 8, v208
	v_add_u32_e32 v0, 0x400, v0
	s_mov_b32 s5, 0
